# indexer head loop software-pipelined inside the wave: relu and weighted-sum VALU of head h-1 interleaved with the MFMAs of head h (two score accumulator sets), query fragments and head weights prefetc
# speedup vs baseline: 1.0249x; 1.0041x over previous
.LBB0_615:
	ds_read_b128 v[238:241], v132
	ds_read_b128 v[242:245], v132 offset:16
	ds_read_b128 v[246:249], v132 offset:32
	ds_read_b128 v[250:253], v132 offset:48
	ds_read_b128 v[166:169], v69
	ds_read_b128 v[170:173], v69 offset:32
	ds_read_b128 v[174:177], v69 offset:64
	ds_read_b128 v[178:181], v69 offset:96
	s_setprio 1
	s_waitcnt lgkmcnt(3)
	s_waitcnt vmcnt(7)
	v_mfma_f32_32x32x16_f16 v[2:17], v[34:37], v[166:169], 0
	s_waitcnt vmcnt(5)
	v_mfma_f32_32x32x16_f16 v[18:33], v[42:45], v[166:169], 0
	ds_read_b128 v[166:169], v69 offset:128
	s_waitcnt lgkmcnt(3)
	v_mfma_f32_32x32x16_f16 v[2:17], v[38:41], v[170:173], v[2:17]
	s_waitcnt vmcnt(4)
	v_mfma_f32_32x32x16_f16 v[18:33], v[46:49], v[170:173], v[18:33]
	ds_read_b128 v[170:173], v69 offset:160
	s_waitcnt lgkmcnt(3)
	s_waitcnt vmcnt(3)
	v_mfma_f32_32x32x16_f16 v[2:17], v[50:53], v[174:177], v[2:17]
	s_waitcnt vmcnt(1)
	v_mfma_f32_32x32x16_f16 v[18:33], v[58:61], v[174:177], v[18:33]
	ds_read_b128 v[174:177], v69 offset:192
	s_waitcnt lgkmcnt(3)
	v_mfma_f32_32x32x16_f16 v[2:17], v[54:57], v[178:181], v[2:17]
	s_waitcnt vmcnt(0)
	v_mfma_f32_32x32x16_f16 v[18:33], v[62:65], v[178:181], v[18:33]
	ds_read_b128 v[178:181], v69 offset:224
	s_waitcnt lgkmcnt(3)
	v_mfma_f32_32x32x16_f16 v[182:197], v[34:37], v[166:169], 0
	s_nop 1
	v_max_f32_e32 v2, 0, v2
	v_max_f32_e32 v3, 0, v3
	v_max_f32_e32 v4, 0, v4
	v_max_f32_e32 v5, 0, v5
	v_max_f32_e32 v6, 0, v6
	v_max_f32_e32 v7, 0, v7
	v_mfma_f32_32x32x16_f16 v[222:237], v[42:45], v[166:169], 0
	ds_read_b128 v[166:169], v69 offset:256
	v_max_f32_e32 v8, 0, v8
	v_max_f32_e32 v9, 0, v9
	v_max_f32_e32 v10, 0, v10
	v_max_f32_e32 v11, 0, v11
	v_max_f32_e32 v12, 0, v12
	v_max_f32_e32 v13, 0, v13
	s_waitcnt lgkmcnt(3)
	v_mfma_f32_32x32x16_f16 v[182:197], v[38:41], v[170:173], v[182:197]
	v_max_f32_e32 v14, 0, v14
	v_max_f32_e32 v15, 0, v15
	v_max_f32_e32 v16, 0, v16
	v_max_f32_e32 v17, 0, v17
	v_max_f32_e32 v18, 0, v18
	v_max_f32_e32 v19, 0, v19
	v_mfma_f32_32x32x16_f16 v[222:237], v[46:49], v[170:173], v[222:237]
	ds_read_b128 v[170:173], v69 offset:288
	v_max_f32_e32 v20, 0, v20
	v_max_f32_e32 v21, 0, v21
	v_max_f32_e32 v22, 0, v22
	v_max_f32_e32 v23, 0, v23
	v_max_f32_e32 v24, 0, v24
	v_max_f32_e32 v25, 0, v25
	s_waitcnt lgkmcnt(3)
	v_mfma_f32_32x32x16_f16 v[182:197], v[50:53], v[174:177], v[182:197]
	v_max_f32_e32 v26, 0, v26
	v_max_f32_e32 v27, 0, v27
	v_max_f32_e32 v28, 0, v28
	v_max_f32_e32 v29, 0, v29
	v_max_f32_e32 v30, 0, v30
	v_max_f32_e32 v31, 0, v31
	v_mfma_f32_32x32x16_f16 v[222:237], v[58:61], v[174:177], v[222:237]
	ds_read_b128 v[174:177], v69 offset:320
	v_max_f32_e32 v32, 0, v32
	v_max_f32_e32 v33, 0, v33
	v_pk_fma_f32 v[108:109], v[238:239], v[2:3], v[108:109] op_sel_hi:[0,1,1]
	v_pk_fma_f32 v[110:111], v[238:239], v[4:5], v[110:111] op_sel_hi:[0,1,1]
	v_pk_fma_f32 v[104:105], v[238:239], v[6:7], v[104:105] op_sel_hi:[0,1,1]
	v_pk_fma_f32 v[106:107], v[238:239], v[8:9], v[106:107] op_sel_hi:[0,1,1]
	s_waitcnt lgkmcnt(3)
	v_mfma_f32_32x32x16_f16 v[182:197], v[54:57], v[178:181], v[182:197]
	v_pk_fma_f32 v[100:101], v[238:239], v[10:11], v[100:101] op_sel_hi:[0,1,1]
	v_pk_fma_f32 v[102:103], v[238:239], v[12:13], v[102:103] op_sel_hi:[0,1,1]
	v_pk_fma_f32 v[98:99], v[238:239], v[14:15], v[98:99] op_sel_hi:[0,1,1]
	v_pk_fma_f32 v[84:85], v[238:239], v[16:17], v[84:85] op_sel_hi:[0,1,1]
	v_pk_fma_f32 v[94:95], v[238:239], v[18:19], v[94:95] op_sel_hi:[0,1,1]
	v_pk_fma_f32 v[96:97], v[238:239], v[20:21], v[96:97] op_sel_hi:[0,1,1]
	v_mfma_f32_32x32x16_f16 v[222:237], v[62:65], v[178:181], v[222:237]
	ds_read_b128 v[178:181], v69 offset:352
	v_pk_fma_f32 v[90:91], v[238:239], v[22:23], v[90:91] op_sel_hi:[0,1,1]
	v_pk_fma_f32 v[92:93], v[238:239], v[24:25], v[92:93] op_sel_hi:[0,1,1]
	v_pk_fma_f32 v[86:87], v[238:239], v[26:27], v[86:87] op_sel_hi:[0,1,1]
	v_pk_fma_f32 v[88:89], v[238:239], v[28:29], v[88:89] op_sel_hi:[0,1,1]
	v_pk_fma_f32 v[82:83], v[238:239], v[30:31], v[82:83] op_sel_hi:[0,1,1]
	v_pk_fma_f32 v[78:79], v[238:239], v[32:33], v[78:79] op_sel_hi:[0,1,1]
	s_waitcnt lgkmcnt(3)
	v_mfma_f32_32x32x16_f16 v[2:17], v[34:37], v[166:169], 0
	s_nop 1
	v_max_f32_e32 v182, 0, v182
	v_max_f32_e32 v183, 0, v183
	v_max_f32_e32 v184, 0, v184
	v_max_f32_e32 v185, 0, v185
	v_max_f32_e32 v186, 0, v186
	v_max_f32_e32 v187, 0, v187
	v_mfma_f32_32x32x16_f16 v[18:33], v[42:45], v[166:169], 0
	ds_read_b128 v[166:169], v69 offset:384
	v_max_f32_e32 v188, 0, v188
	v_max_f32_e32 v189, 0, v189
	v_max_f32_e32 v190, 0, v190
	v_max_f32_e32 v191, 0, v191
	v_max_f32_e32 v192, 0, v192
	v_max_f32_e32 v193, 0, v193
	s_waitcnt lgkmcnt(3)
	v_mfma_f32_32x32x16_f16 v[2:17], v[38:41], v[170:173], v[2:17]
	v_max_f32_e32 v194, 0, v194
	v_max_f32_e32 v195, 0, v195
	v_max_f32_e32 v196, 0, v196
	v_max_f32_e32 v197, 0, v197
	v_max_f32_e32 v222, 0, v222
	v_max_f32_e32 v223, 0, v223
	v_mfma_f32_32x32x16_f16 v[18:33], v[46:49], v[170:173], v[18:33]
	ds_read_b128 v[170:173], v69 offset:416
	v_max_f32_e32 v224, 0, v224
	v_max_f32_e32 v225, 0, v225
	v_max_f32_e32 v226, 0, v226
	v_max_f32_e32 v227, 0, v227
	v_max_f32_e32 v228, 0, v228
	v_max_f32_e32 v229, 0, v229
	s_waitcnt lgkmcnt(3)
	v_mfma_f32_32x32x16_f16 v[2:17], v[50:53], v[174:177], v[2:17]
	v_max_f32_e32 v230, 0, v230
	v_max_f32_e32 v231, 0, v231
	v_max_f32_e32 v232, 0, v232
	v_max_f32_e32 v233, 0, v233
	v_max_f32_e32 v234, 0, v234
	v_max_f32_e32 v235, 0, v235
	v_mfma_f32_32x32x16_f16 v[18:33], v[58:61], v[174:177], v[18:33]
	ds_read_b128 v[174:177], v69 offset:448
	v_max_f32_e32 v236, 0, v236
	v_max_f32_e32 v237, 0, v237
	v_pk_fma_f32 v[108:109], v[238:239], v[182:183], v[108:109] op_sel:[1,0,0] op_sel_hi:[1,1,1]
	v_pk_fma_f32 v[110:111], v[238:239], v[184:185], v[110:111] op_sel:[1,0,0] op_sel_hi:[1,1,1]
	v_pk_fma_f32 v[104:105], v[238:239], v[186:187], v[104:105] op_sel:[1,0,0] op_sel_hi:[1,1,1]
	v_pk_fma_f32 v[106:107], v[238:239], v[188:189], v[106:107] op_sel:[1,0,0] op_sel_hi:[1,1,1]
	s_waitcnt lgkmcnt(3)
	v_mfma_f32_32x32x16_f16 v[2:17], v[54:57], v[178:181], v[2:17]
	v_pk_fma_f32 v[100:101], v[238:239], v[190:191], v[100:101] op_sel:[1,0,0] op_sel_hi:[1,1,1]
	v_pk_fma_f32 v[102:103], v[238:239], v[192:193], v[102:103] op_sel:[1,0,0] op_sel_hi:[1,1,1]
	v_pk_fma_f32 v[98:99], v[238:239], v[194:195], v[98:99] op_sel:[1,0,0] op_sel_hi:[1,1,1]
	v_pk_fma_f32 v[84:85], v[238:239], v[196:197], v[84:85] op_sel:[1,0,0] op_sel_hi:[1,1,1]
	v_pk_fma_f32 v[94:95], v[238:239], v[222:223], v[94:95] op_sel:[1,0,0] op_sel_hi:[1,1,1]
	v_pk_fma_f32 v[96:97], v[238:239], v[224:225], v[96:97] op_sel:[1,0,0] op_sel_hi:[1,1,1]
	v_mfma_f32_32x32x16_f16 v[18:33], v[62:65], v[178:181], v[18:33]
	ds_read_b128 v[178:181], v69 offset:480
	v_pk_fma_f32 v[90:91], v[238:239], v[226:227], v[90:91] op_sel:[1,0,0] op_sel_hi:[1,1,1]
	v_pk_fma_f32 v[92:93], v[238:239], v[228:229], v[92:93] op_sel:[1,0,0] op_sel_hi:[1,1,1]
	v_pk_fma_f32 v[86:87], v[238:239], v[230:231], v[86:87] op_sel:[1,0,0] op_sel_hi:[1,1,1]
	v_pk_fma_f32 v[88:89], v[238:239], v[232:233], v[88:89] op_sel:[1,0,0] op_sel_hi:[1,1,1]
	v_pk_fma_f32 v[82:83], v[238:239], v[234:235], v[82:83] op_sel:[1,0,0] op_sel_hi:[1,1,1]
	v_pk_fma_f32 v[78:79], v[238:239], v[236:237], v[78:79] op_sel:[1,0,0] op_sel_hi:[1,1,1]
	s_waitcnt lgkmcnt(3)
	v_mfma_f32_32x32x16_f16 v[182:197], v[34:37], v[166:169], 0
	s_nop 1
	v_max_f32_e32 v2, 0, v2
	v_max_f32_e32 v3, 0, v3
	v_max_f32_e32 v4, 0, v4
	v_max_f32_e32 v5, 0, v5
	v_max_f32_e32 v6, 0, v6
	v_max_f32_e32 v7, 0, v7
	v_mfma_f32_32x32x16_f16 v[222:237], v[42:45], v[166:169], 0
	ds_read_b128 v[166:169], v69 offset:512
	v_max_f32_e32 v8, 0, v8
	v_max_f32_e32 v9, 0, v9
	v_max_f32_e32 v10, 0, v10
	v_max_f32_e32 v11, 0, v11
	v_max_f32_e32 v12, 0, v12
	v_max_f32_e32 v13, 0, v13
	s_waitcnt lgkmcnt(3)
	v_mfma_f32_32x32x16_f16 v[182:197], v[38:41], v[170:173], v[182:197]
	v_max_f32_e32 v14, 0, v14
	v_max_f32_e32 v15, 0, v15
	v_max_f32_e32 v16, 0, v16
	v_max_f32_e32 v17, 0, v17
	v_max_f32_e32 v18, 0, v18
	v_max_f32_e32 v19, 0, v19
	v_mfma_f32_32x32x16_f16 v[222:237], v[46:49], v[170:173], v[222:237]
	ds_read_b128 v[170:173], v69 offset:544
	v_max_f32_e32 v20, 0, v20
	v_max_f32_e32 v21, 0, v21
	v_max_f32_e32 v22, 0, v22
	v_max_f32_e32 v23, 0, v23
	v_max_f32_e32 v24, 0, v24
	v_max_f32_e32 v25, 0, v25
	s_waitcnt lgkmcnt(3)
	v_mfma_f32_32x32x16_f16 v[182:197], v[50:53], v[174:177], v[182:197]
	v_max_f32_e32 v26, 0, v26
	v_max_f32_e32 v27, 0, v27
	v_max_f32_e32 v28, 0, v28
	v_max_f32_e32 v29, 0, v29
	v_max_f32_e32 v30, 0, v30
	v_max_f32_e32 v31, 0, v31
	v_mfma_f32_32x32x16_f16 v[222:237], v[58:61], v[174:177], v[222:237]
	ds_read_b128 v[174:177], v69 offset:576
	v_max_f32_e32 v32, 0, v32
	v_max_f32_e32 v33, 0, v33
	v_pk_fma_f32 v[108:109], v[240:241], v[2:3], v[108:109] op_sel_hi:[0,1,1]
	v_pk_fma_f32 v[110:111], v[240:241], v[4:5], v[110:111] op_sel_hi:[0,1,1]
	v_pk_fma_f32 v[104:105], v[240:241], v[6:7], v[104:105] op_sel_hi:[0,1,1]
	v_pk_fma_f32 v[106:107], v[240:241], v[8:9], v[106:107] op_sel_hi:[0,1,1]
	s_waitcnt lgkmcnt(3)
	v_mfma_f32_32x32x16_f16 v[182:197], v[54:57], v[178:181], v[182:197]
	v_pk_fma_f32 v[100:101], v[240:241], v[10:11], v[100:101] op_sel_hi:[0,1,1]
	v_pk_fma_f32 v[102:103], v[240:241], v[12:13], v[102:103] op_sel_hi:[0,1,1]
	v_pk_fma_f32 v[98:99], v[240:241], v[14:15], v[98:99] op_sel_hi:[0,1,1]
	v_pk_fma_f32 v[84:85], v[240:241], v[16:17], v[84:85] op_sel_hi:[0,1,1]
	v_pk_fma_f32 v[94:95], v[240:241], v[18:19], v[94:95] op_sel_hi:[0,1,1]
	v_pk_fma_f32 v[96:97], v[240:241], v[20:21], v[96:97] op_sel_hi:[0,1,1]
	v_mfma_f32_32x32x16_f16 v[222:237], v[62:65], v[178:181], v[222:237]
	ds_read_b128 v[178:181], v69 offset:608
	v_pk_fma_f32 v[90:91], v[240:241], v[22:23], v[90:91] op_sel_hi:[0,1,1]
	v_pk_fma_f32 v[92:93], v[240:241], v[24:25], v[92:93] op_sel_hi:[0,1,1]
	v_pk_fma_f32 v[86:87], v[240:241], v[26:27], v[86:87] op_sel_hi:[0,1,1]
	v_pk_fma_f32 v[88:89], v[240:241], v[28:29], v[88:89] op_sel_hi:[0,1,1]
	v_pk_fma_f32 v[82:83], v[240:241], v[30:31], v[82:83] op_sel_hi:[0,1,1]
	v_pk_fma_f32 v[78:79], v[240:241], v[32:33], v[78:79] op_sel_hi:[0,1,1]
	s_waitcnt lgkmcnt(3)
	v_mfma_f32_32x32x16_f16 v[2:17], v[34:37], v[166:169], 0
	s_nop 1
	v_max_f32_e32 v182, 0, v182
	v_max_f32_e32 v183, 0, v183
	v_max_f32_e32 v184, 0, v184
	v_max_f32_e32 v185, 0, v185
	v_max_f32_e32 v186, 0, v186
	v_max_f32_e32 v187, 0, v187
	v_mfma_f32_32x32x16_f16 v[18:33], v[42:45], v[166:169], 0
	ds_read_b128 v[166:169], v69 offset:640
	v_max_f32_e32 v188, 0, v188
	v_max_f32_e32 v189, 0, v189
	v_max_f32_e32 v190, 0, v190
	v_max_f32_e32 v191, 0, v191
	v_max_f32_e32 v192, 0, v192
	v_max_f32_e32 v193, 0, v193
	s_waitcnt lgkmcnt(3)
	v_mfma_f32_32x32x16_f16 v[2:17], v[38:41], v[170:173], v[2:17]
	v_max_f32_e32 v194, 0, v194
	v_max_f32_e32 v195, 0, v195
	v_max_f32_e32 v196, 0, v196
	v_max_f32_e32 v197, 0, v197
	v_max_f32_e32 v222, 0, v222
	v_max_f32_e32 v223, 0, v223
	v_mfma_f32_32x32x16_f16 v[18:33], v[46:49], v[170:173], v[18:33]
	ds_read_b128 v[170:173], v69 offset:672
	v_max_f32_e32 v224, 0, v224
	v_max_f32_e32 v225, 0, v225
	v_max_f32_e32 v226, 0, v226
	v_max_f32_e32 v227, 0, v227
	v_max_f32_e32 v228, 0, v228
	v_max_f32_e32 v229, 0, v229
	s_waitcnt lgkmcnt(3)
	v_mfma_f32_32x32x16_f16 v[2:17], v[50:53], v[174:177], v[2:17]
	v_max_f32_e32 v230, 0, v230
	v_max_f32_e32 v231, 0, v231
	v_max_f32_e32 v232, 0, v232
	v_max_f32_e32 v233, 0, v233
	v_max_f32_e32 v234, 0, v234
	v_max_f32_e32 v235, 0, v235
	v_mfma_f32_32x32x16_f16 v[18:33], v[58:61], v[174:177], v[18:33]
	ds_read_b128 v[174:177], v69 offset:704
	v_max_f32_e32 v236, 0, v236
	v_max_f32_e32 v237, 0, v237
	v_pk_fma_f32 v[108:109], v[240:241], v[182:183], v[108:109] op_sel:[1,0,0] op_sel_hi:[1,1,1]
	v_pk_fma_f32 v[110:111], v[240:241], v[184:185], v[110:111] op_sel:[1,0,0] op_sel_hi:[1,1,1]
	v_pk_fma_f32 v[104:105], v[240:241], v[186:187], v[104:105] op_sel:[1,0,0] op_sel_hi:[1,1,1]
	v_pk_fma_f32 v[106:107], v[240:241], v[188:189], v[106:107] op_sel:[1,0,0] op_sel_hi:[1,1,1]
	s_waitcnt lgkmcnt(3)
	v_mfma_f32_32x32x16_f16 v[2:17], v[54:57], v[178:181], v[2:17]
	v_pk_fma_f32 v[100:101], v[240:241], v[190:191], v[100:101] op_sel:[1,0,0] op_sel_hi:[1,1,1]
	v_pk_fma_f32 v[102:103], v[240:241], v[192:193], v[102:103] op_sel:[1,0,0] op_sel_hi:[1,1,1]
	v_pk_fma_f32 v[98:99], v[240:241], v[194:195], v[98:99] op_sel:[1,0,0] op_sel_hi:[1,1,1]
	v_pk_fma_f32 v[84:85], v[240:241], v[196:197], v[84:85] op_sel:[1,0,0] op_sel_hi:[1,1,1]
	v_pk_fma_f32 v[94:95], v[240:241], v[222:223], v[94:95] op_sel:[1,0,0] op_sel_hi:[1,1,1]
	v_pk_fma_f32 v[96:97], v[240:241], v[224:225], v[96:97] op_sel:[1,0,0] op_sel_hi:[1,1,1]
	v_mfma_f32_32x32x16_f16 v[18:33], v[62:65], v[178:181], v[18:33]
	ds_read_b128 v[178:181], v69 offset:736
	v_pk_fma_f32 v[90:91], v[240:241], v[226:227], v[90:91] op_sel:[1,0,0] op_sel_hi:[1,1,1]
	v_pk_fma_f32 v[92:93], v[240:241], v[228:229], v[92:93] op_sel:[1,0,0] op_sel_hi:[1,1,1]
	v_pk_fma_f32 v[86:87], v[240:241], v[230:231], v[86:87] op_sel:[1,0,0] op_sel_hi:[1,1,1]
	v_pk_fma_f32 v[88:89], v[240:241], v[232:233], v[88:89] op_sel:[1,0,0] op_sel_hi:[1,1,1]
	v_pk_fma_f32 v[82:83], v[240:241], v[234:235], v[82:83] op_sel:[1,0,0] op_sel_hi:[1,1,1]
	v_pk_fma_f32 v[78:79], v[240:241], v[236:237], v[78:79] op_sel:[1,0,0] op_sel_hi:[1,1,1]
	s_waitcnt lgkmcnt(3)
	v_mfma_f32_32x32x16_f16 v[182:197], v[34:37], v[166:169], 0
	s_nop 1
	v_max_f32_e32 v2, 0, v2
	v_max_f32_e32 v3, 0, v3
	v_max_f32_e32 v4, 0, v4
	v_max_f32_e32 v5, 0, v5
	v_max_f32_e32 v6, 0, v6
	v_max_f32_e32 v7, 0, v7
	v_mfma_f32_32x32x16_f16 v[222:237], v[42:45], v[166:169], 0
	ds_read_b128 v[166:169], v69 offset:768
	v_max_f32_e32 v8, 0, v8
	v_max_f32_e32 v9, 0, v9
	v_max_f32_e32 v10, 0, v10
	v_max_f32_e32 v11, 0, v11
	v_max_f32_e32 v12, 0, v12
	v_max_f32_e32 v13, 0, v13
	s_waitcnt lgkmcnt(3)
	v_mfma_f32_32x32x16_f16 v[182:197], v[38:41], v[170:173], v[182:197]
	v_max_f32_e32 v14, 0, v14
	v_max_f32_e32 v15, 0, v15
	v_max_f32_e32 v16, 0, v16
	v_max_f32_e32 v17, 0, v17
	v_max_f32_e32 v18, 0, v18
	v_max_f32_e32 v19, 0, v19
	v_mfma_f32_32x32x16_f16 v[222:237], v[46:49], v[170:173], v[222:237]
	ds_read_b128 v[170:173], v69 offset:800
	v_max_f32_e32 v20, 0, v20
	v_max_f32_e32 v21, 0, v21
	v_max_f32_e32 v22, 0, v22
	v_max_f32_e32 v23, 0, v23
	v_max_f32_e32 v24, 0, v24
	v_max_f32_e32 v25, 0, v25
	s_waitcnt lgkmcnt(3)
	v_mfma_f32_32x32x16_f16 v[182:197], v[50:53], v[174:177], v[182:197]
	v_max_f32_e32 v26, 0, v26
	v_max_f32_e32 v27, 0, v27
	v_max_f32_e32 v28, 0, v28
	v_max_f32_e32 v29, 0, v29
	v_max_f32_e32 v30, 0, v30
	v_max_f32_e32 v31, 0, v31
	v_mfma_f32_32x32x16_f16 v[222:237], v[58:61], v[174:177], v[222:237]
	ds_read_b128 v[174:177], v69 offset:832
	v_max_f32_e32 v32, 0, v32
	v_max_f32_e32 v33, 0, v33
	v_pk_fma_f32 v[108:109], v[242:243], v[2:3], v[108:109] op_sel_hi:[0,1,1]
	v_pk_fma_f32 v[110:111], v[242:243], v[4:5], v[110:111] op_sel_hi:[0,1,1]
	v_pk_fma_f32 v[104:105], v[242:243], v[6:7], v[104:105] op_sel_hi:[0,1,1]
	v_pk_fma_f32 v[106:107], v[242:243], v[8:9], v[106:107] op_sel_hi:[0,1,1]
	s_waitcnt lgkmcnt(3)
	v_mfma_f32_32x32x16_f16 v[182:197], v[54:57], v[178:181], v[182:197]
	v_pk_fma_f32 v[100:101], v[242:243], v[10:11], v[100:101] op_sel_hi:[0,1,1]
	v_pk_fma_f32 v[102:103], v[242:243], v[12:13], v[102:103] op_sel_hi:[0,1,1]
	v_pk_fma_f32 v[98:99], v[242:243], v[14:15], v[98:99] op_sel_hi:[0,1,1]
	v_pk_fma_f32 v[84:85], v[242:243], v[16:17], v[84:85] op_sel_hi:[0,1,1]
	v_pk_fma_f32 v[94:95], v[242:243], v[18:19], v[94:95] op_sel_hi:[0,1,1]
	v_pk_fma_f32 v[96:97], v[242:243], v[20:21], v[96:97] op_sel_hi:[0,1,1]
	v_mfma_f32_32x32x16_f16 v[222:237], v[62:65], v[178:181], v[222:237]
	ds_read_b128 v[178:181], v69 offset:864
	v_pk_fma_f32 v[90:91], v[242:243], v[22:23], v[90:91] op_sel_hi:[0,1,1]
	v_pk_fma_f32 v[92:93], v[242:243], v[24:25], v[92:93] op_sel_hi:[0,1,1]
	v_pk_fma_f32 v[86:87], v[242:243], v[26:27], v[86:87] op_sel_hi:[0,1,1]
	v_pk_fma_f32 v[88:89], v[242:243], v[28:29], v[88:89] op_sel_hi:[0,1,1]
	v_pk_fma_f32 v[82:83], v[242:243], v[30:31], v[82:83] op_sel_hi:[0,1,1]
	v_pk_fma_f32 v[78:79], v[242:243], v[32:33], v[78:79] op_sel_hi:[0,1,1]
	s_waitcnt lgkmcnt(3)
	v_mfma_f32_32x32x16_f16 v[2:17], v[34:37], v[166:169], 0
	s_nop 1
	v_max_f32_e32 v182, 0, v182
	v_max_f32_e32 v183, 0, v183
	v_max_f32_e32 v184, 0, v184
	v_max_f32_e32 v185, 0, v185
	v_max_f32_e32 v186, 0, v186
	v_max_f32_e32 v187, 0, v187
	v_mfma_f32_32x32x16_f16 v[18:33], v[42:45], v[166:169], 0
	ds_read_b128 v[166:169], v69 offset:896
	v_max_f32_e32 v188, 0, v188
	v_max_f32_e32 v189, 0, v189
	v_max_f32_e32 v190, 0, v190
	v_max_f32_e32 v191, 0, v191
	v_max_f32_e32 v192, 0, v192
	v_max_f32_e32 v193, 0, v193
	s_waitcnt lgkmcnt(3)
	v_mfma_f32_32x32x16_f16 v[2:17], v[38:41], v[170:173], v[2:17]
	v_max_f32_e32 v194, 0, v194
	v_max_f32_e32 v195, 0, v195
	v_max_f32_e32 v196, 0, v196
	v_max_f32_e32 v197, 0, v197
	v_max_f32_e32 v222, 0, v222
	v_max_f32_e32 v223, 0, v223
	v_mfma_f32_32x32x16_f16 v[18:33], v[46:49], v[170:173], v[18:33]
	ds_read_b128 v[170:173], v69 offset:928
	v_max_f32_e32 v224, 0, v224
	v_max_f32_e32 v225, 0, v225
	v_max_f32_e32 v226, 0, v226
	v_max_f32_e32 v227, 0, v227
	v_max_f32_e32 v228, 0, v228
	v_max_f32_e32 v229, 0, v229
	s_waitcnt lgkmcnt(3)
	v_mfma_f32_32x32x16_f16 v[2:17], v[50:53], v[174:177], v[2:17]
	v_max_f32_e32 v230, 0, v230
	v_max_f32_e32 v231, 0, v231
	v_max_f32_e32 v232, 0, v232
	v_max_f32_e32 v233, 0, v233
	v_max_f32_e32 v234, 0, v234
	v_max_f32_e32 v235, 0, v235
	v_mfma_f32_32x32x16_f16 v[18:33], v[58:61], v[174:177], v[18:33]
	ds_read_b128 v[174:177], v69 offset:960
	v_max_f32_e32 v236, 0, v236
	v_max_f32_e32 v237, 0, v237
	v_pk_fma_f32 v[108:109], v[242:243], v[182:183], v[108:109] op_sel:[1,0,0] op_sel_hi:[1,1,1]
	v_pk_fma_f32 v[110:111], v[242:243], v[184:185], v[110:111] op_sel:[1,0,0] op_sel_hi:[1,1,1]
	v_pk_fma_f32 v[104:105], v[242:243], v[186:187], v[104:105] op_sel:[1,0,0] op_sel_hi:[1,1,1]
	v_pk_fma_f32 v[106:107], v[242:243], v[188:189], v[106:107] op_sel:[1,0,0] op_sel_hi:[1,1,1]
	s_waitcnt lgkmcnt(3)
	v_mfma_f32_32x32x16_f16 v[2:17], v[54:57], v[178:181], v[2:17]
	v_pk_fma_f32 v[100:101], v[242:243], v[190:191], v[100:101] op_sel:[1,0,0] op_sel_hi:[1,1,1]
	v_pk_fma_f32 v[102:103], v[242:243], v[192:193], v[102:103] op_sel:[1,0,0] op_sel_hi:[1,1,1]
	v_pk_fma_f32 v[98:99], v[242:243], v[194:195], v[98:99] op_sel:[1,0,0] op_sel_hi:[1,1,1]
	v_pk_fma_f32 v[84:85], v[242:243], v[196:197], v[84:85] op_sel:[1,0,0] op_sel_hi:[1,1,1]
	v_pk_fma_f32 v[94:95], v[242:243], v[222:223], v[94:95] op_sel:[1,0,0] op_sel_hi:[1,1,1]
	v_pk_fma_f32 v[96:97], v[242:243], v[224:225], v[96:97] op_sel:[1,0,0] op_sel_hi:[1,1,1]
	v_mfma_f32_32x32x16_f16 v[18:33], v[62:65], v[178:181], v[18:33]
	ds_read_b128 v[178:181], v69 offset:992
	v_pk_fma_f32 v[90:91], v[242:243], v[226:227], v[90:91] op_sel:[1,0,0] op_sel_hi:[1,1,1]
	v_pk_fma_f32 v[92:93], v[242:243], v[228:229], v[92:93] op_sel:[1,0,0] op_sel_hi:[1,1,1]
	v_pk_fma_f32 v[86:87], v[242:243], v[230:231], v[86:87] op_sel:[1,0,0] op_sel_hi:[1,1,1]
	v_pk_fma_f32 v[88:89], v[242:243], v[232:233], v[88:89] op_sel:[1,0,0] op_sel_hi:[1,1,1]
	v_pk_fma_f32 v[82:83], v[242:243], v[234:235], v[82:83] op_sel:[1,0,0] op_sel_hi:[1,1,1]
	v_pk_fma_f32 v[78:79], v[242:243], v[236:237], v[78:79] op_sel:[1,0,0] op_sel_hi:[1,1,1]
	s_waitcnt lgkmcnt(3)
	v_mfma_f32_32x32x16_f16 v[182:197], v[34:37], v[166:169], 0
	s_nop 1
	v_max_f32_e32 v2, 0, v2
	v_max_f32_e32 v3, 0, v3
	v_max_f32_e32 v4, 0, v4
	v_max_f32_e32 v5, 0, v5
	v_max_f32_e32 v6, 0, v6
	v_max_f32_e32 v7, 0, v7
	v_mfma_f32_32x32x16_f16 v[222:237], v[42:45], v[166:169], 0
	ds_read_b128 v[166:169], v69 offset:1024
	v_max_f32_e32 v8, 0, v8
	v_max_f32_e32 v9, 0, v9
	v_max_f32_e32 v10, 0, v10
	v_max_f32_e32 v11, 0, v11
	v_max_f32_e32 v12, 0, v12
	v_max_f32_e32 v13, 0, v13
	s_waitcnt lgkmcnt(3)
	v_mfma_f32_32x32x16_f16 v[182:197], v[38:41], v[170:173], v[182:197]
	v_max_f32_e32 v14, 0, v14
	v_max_f32_e32 v15, 0, v15
	v_max_f32_e32 v16, 0, v16
	v_max_f32_e32 v17, 0, v17
	v_max_f32_e32 v18, 0, v18
	v_max_f32_e32 v19, 0, v19
	v_mfma_f32_32x32x16_f16 v[222:237], v[46:49], v[170:173], v[222:237]
	ds_read_b128 v[170:173], v69 offset:1056
	v_max_f32_e32 v20, 0, v20
	v_max_f32_e32 v21, 0, v21
	v_max_f32_e32 v22, 0, v22
	v_max_f32_e32 v23, 0, v23
	v_max_f32_e32 v24, 0, v24
	v_max_f32_e32 v25, 0, v25
	s_waitcnt lgkmcnt(3)
	v_mfma_f32_32x32x16_f16 v[182:197], v[50:53], v[174:177], v[182:197]
	v_max_f32_e32 v26, 0, v26
	v_max_f32_e32 v27, 0, v27
	v_max_f32_e32 v28, 0, v28
	v_max_f32_e32 v29, 0, v29
	v_max_f32_e32 v30, 0, v30
	v_max_f32_e32 v31, 0, v31
	v_mfma_f32_32x32x16_f16 v[222:237], v[58:61], v[174:177], v[222:237]
	ds_read_b128 v[174:177], v69 offset:1088
	v_max_f32_e32 v32, 0, v32
	v_max_f32_e32 v33, 0, v33
	v_pk_fma_f32 v[108:109], v[244:245], v[2:3], v[108:109] op_sel_hi:[0,1,1]
	v_pk_fma_f32 v[110:111], v[244:245], v[4:5], v[110:111] op_sel_hi:[0,1,1]
	v_pk_fma_f32 v[104:105], v[244:245], v[6:7], v[104:105] op_sel_hi:[0,1,1]
	v_pk_fma_f32 v[106:107], v[244:245], v[8:9], v[106:107] op_sel_hi:[0,1,1]
	s_waitcnt lgkmcnt(3)
	v_mfma_f32_32x32x16_f16 v[182:197], v[54:57], v[178:181], v[182:197]
	v_pk_fma_f32 v[100:101], v[244:245], v[10:11], v[100:101] op_sel_hi:[0,1,1]
	v_pk_fma_f32 v[102:103], v[244:245], v[12:13], v[102:103] op_sel_hi:[0,1,1]
	v_pk_fma_f32 v[98:99], v[244:245], v[14:15], v[98:99] op_sel_hi:[0,1,1]
	v_pk_fma_f32 v[84:85], v[244:245], v[16:17], v[84:85] op_sel_hi:[0,1,1]
	v_pk_fma_f32 v[94:95], v[244:245], v[18:19], v[94:95] op_sel_hi:[0,1,1]
	v_pk_fma_f32 v[96:97], v[244:245], v[20:21], v[96:97] op_sel_hi:[0,1,1]
	v_mfma_f32_32x32x16_f16 v[222:237], v[62:65], v[178:181], v[222:237]
	ds_read_b128 v[178:181], v69 offset:1120
	v_pk_fma_f32 v[90:91], v[244:245], v[22:23], v[90:91] op_sel_hi:[0,1,1]
	v_pk_fma_f32 v[92:93], v[244:245], v[24:25], v[92:93] op_sel_hi:[0,1,1]
	v_pk_fma_f32 v[86:87], v[244:245], v[26:27], v[86:87] op_sel_hi:[0,1,1]
	v_pk_fma_f32 v[88:89], v[244:245], v[28:29], v[88:89] op_sel_hi:[0,1,1]
	v_pk_fma_f32 v[82:83], v[244:245], v[30:31], v[82:83] op_sel_hi:[0,1,1]
	v_pk_fma_f32 v[78:79], v[244:245], v[32:33], v[78:79] op_sel_hi:[0,1,1]
	s_waitcnt lgkmcnt(3)
	v_mfma_f32_32x32x16_f16 v[2:17], v[34:37], v[166:169], 0
	s_nop 1
	v_max_f32_e32 v182, 0, v182
	v_max_f32_e32 v183, 0, v183
	v_max_f32_e32 v184, 0, v184
	v_max_f32_e32 v185, 0, v185
	v_max_f32_e32 v186, 0, v186
	v_max_f32_e32 v187, 0, v187
	v_mfma_f32_32x32x16_f16 v[18:33], v[42:45], v[166:169], 0
	ds_read_b128 v[166:169], v69 offset:1152
	v_max_f32_e32 v188, 0, v188
	v_max_f32_e32 v189, 0, v189
	v_max_f32_e32 v190, 0, v190
	v_max_f32_e32 v191, 0, v191
	v_max_f32_e32 v192, 0, v192
	v_max_f32_e32 v193, 0, v193
	s_waitcnt lgkmcnt(3)
	v_mfma_f32_32x32x16_f16 v[2:17], v[38:41], v[170:173], v[2:17]
	v_max_f32_e32 v194, 0, v194
	v_max_f32_e32 v195, 0, v195
	v_max_f32_e32 v196, 0, v196
	v_max_f32_e32 v197, 0, v197
	v_max_f32_e32 v222, 0, v222
	v_max_f32_e32 v223, 0, v223
	v_mfma_f32_32x32x16_f16 v[18:33], v[46:49], v[170:173], v[18:33]
	ds_read_b128 v[170:173], v69 offset:1184
	v_max_f32_e32 v224, 0, v224
	v_max_f32_e32 v225, 0, v225
	v_max_f32_e32 v226, 0, v226
	v_max_f32_e32 v227, 0, v227
	v_max_f32_e32 v228, 0, v228
	v_max_f32_e32 v229, 0, v229
	s_waitcnt lgkmcnt(3)
	v_mfma_f32_32x32x16_f16 v[2:17], v[50:53], v[174:177], v[2:17]
	v_max_f32_e32 v230, 0, v230
	v_max_f32_e32 v231, 0, v231
	v_max_f32_e32 v232, 0, v232
	v_max_f32_e32 v233, 0, v233
	v_max_f32_e32 v234, 0, v234
	v_max_f32_e32 v235, 0, v235
	v_mfma_f32_32x32x16_f16 v[18:33], v[58:61], v[174:177], v[18:33]
	ds_read_b128 v[174:177], v69 offset:1216
	v_max_f32_e32 v236, 0, v236
	v_max_f32_e32 v237, 0, v237
	v_pk_fma_f32 v[108:109], v[244:245], v[182:183], v[108:109] op_sel:[1,0,0] op_sel_hi:[1,1,1]
	v_pk_fma_f32 v[110:111], v[244:245], v[184:185], v[110:111] op_sel:[1,0,0] op_sel_hi:[1,1,1]
	v_pk_fma_f32 v[104:105], v[244:245], v[186:187], v[104:105] op_sel:[1,0,0] op_sel_hi:[1,1,1]
	v_pk_fma_f32 v[106:107], v[244:245], v[188:189], v[106:107] op_sel:[1,0,0] op_sel_hi:[1,1,1]
	s_waitcnt lgkmcnt(3)
	v_mfma_f32_32x32x16_f16 v[2:17], v[54:57], v[178:181], v[2:17]
	v_pk_fma_f32 v[100:101], v[244:245], v[190:191], v[100:101] op_sel:[1,0,0] op_sel_hi:[1,1,1]
	v_pk_fma_f32 v[102:103], v[244:245], v[192:193], v[102:103] op_sel:[1,0,0] op_sel_hi:[1,1,1]
	v_pk_fma_f32 v[98:99], v[244:245], v[194:195], v[98:99] op_sel:[1,0,0] op_sel_hi:[1,1,1]
	v_pk_fma_f32 v[84:85], v[244:245], v[196:197], v[84:85] op_sel:[1,0,0] op_sel_hi:[1,1,1]
	v_pk_fma_f32 v[94:95], v[244:245], v[222:223], v[94:95] op_sel:[1,0,0] op_sel_hi:[1,1,1]
	v_pk_fma_f32 v[96:97], v[244:245], v[224:225], v[96:97] op_sel:[1,0,0] op_sel_hi:[1,1,1]
	v_mfma_f32_32x32x16_f16 v[18:33], v[62:65], v[178:181], v[18:33]
	ds_read_b128 v[178:181], v69 offset:1248
	v_pk_fma_f32 v[90:91], v[244:245], v[226:227], v[90:91] op_sel:[1,0,0] op_sel_hi:[1,1,1]
	v_pk_fma_f32 v[92:93], v[244:245], v[228:229], v[92:93] op_sel:[1,0,0] op_sel_hi:[1,1,1]
	v_pk_fma_f32 v[86:87], v[244:245], v[230:231], v[86:87] op_sel:[1,0,0] op_sel_hi:[1,1,1]
	v_pk_fma_f32 v[88:89], v[244:245], v[232:233], v[88:89] op_sel:[1,0,0] op_sel_hi:[1,1,1]
	v_pk_fma_f32 v[82:83], v[244:245], v[234:235], v[82:83] op_sel:[1,0,0] op_sel_hi:[1,1,1]
	v_pk_fma_f32 v[78:79], v[244:245], v[236:237], v[78:79] op_sel:[1,0,0] op_sel_hi:[1,1,1]
	s_waitcnt lgkmcnt(3)
	v_mfma_f32_32x32x16_f16 v[182:197], v[34:37], v[166:169], 0
	s_nop 1
	v_max_f32_e32 v2, 0, v2
	v_max_f32_e32 v3, 0, v3
	v_max_f32_e32 v4, 0, v4
	v_max_f32_e32 v5, 0, v5
	v_max_f32_e32 v6, 0, v6
	v_max_f32_e32 v7, 0, v7
	v_mfma_f32_32x32x16_f16 v[222:237], v[42:45], v[166:169], 0
	ds_read_b128 v[166:169], v69 offset:1280
	v_max_f32_e32 v8, 0, v8
	v_max_f32_e32 v9, 0, v9
	v_max_f32_e32 v10, 0, v10
	v_max_f32_e32 v11, 0, v11
	v_max_f32_e32 v12, 0, v12
	v_max_f32_e32 v13, 0, v13
	s_waitcnt lgkmcnt(3)
	v_mfma_f32_32x32x16_f16 v[182:197], v[38:41], v[170:173], v[182:197]
	v_max_f32_e32 v14, 0, v14
	v_max_f32_e32 v15, 0, v15
	v_max_f32_e32 v16, 0, v16
	v_max_f32_e32 v17, 0, v17
	v_max_f32_e32 v18, 0, v18
	v_max_f32_e32 v19, 0, v19
	v_mfma_f32_32x32x16_f16 v[222:237], v[46:49], v[170:173], v[222:237]
	ds_read_b128 v[170:173], v69 offset:1312
	v_max_f32_e32 v20, 0, v20
	v_max_f32_e32 v21, 0, v21
	v_max_f32_e32 v22, 0, v22
	v_max_f32_e32 v23, 0, v23
	v_max_f32_e32 v24, 0, v24
	v_max_f32_e32 v25, 0, v25
	s_waitcnt lgkmcnt(3)
	v_mfma_f32_32x32x16_f16 v[182:197], v[50:53], v[174:177], v[182:197]
	v_max_f32_e32 v26, 0, v26
	v_max_f32_e32 v27, 0, v27
	v_max_f32_e32 v28, 0, v28
	v_max_f32_e32 v29, 0, v29
	v_max_f32_e32 v30, 0, v30
	v_max_f32_e32 v31, 0, v31
	v_mfma_f32_32x32x16_f16 v[222:237], v[58:61], v[174:177], v[222:237]
	ds_read_b128 v[174:177], v69 offset:1344
	v_max_f32_e32 v32, 0, v32
	v_max_f32_e32 v33, 0, v33
	v_pk_fma_f32 v[108:109], v[246:247], v[2:3], v[108:109] op_sel_hi:[0,1,1]
	v_pk_fma_f32 v[110:111], v[246:247], v[4:5], v[110:111] op_sel_hi:[0,1,1]
	v_pk_fma_f32 v[104:105], v[246:247], v[6:7], v[104:105] op_sel_hi:[0,1,1]
	v_pk_fma_f32 v[106:107], v[246:247], v[8:9], v[106:107] op_sel_hi:[0,1,1]
	s_waitcnt lgkmcnt(3)
	v_mfma_f32_32x32x16_f16 v[182:197], v[54:57], v[178:181], v[182:197]
	v_pk_fma_f32 v[100:101], v[246:247], v[10:11], v[100:101] op_sel_hi:[0,1,1]
	v_pk_fma_f32 v[102:103], v[246:247], v[12:13], v[102:103] op_sel_hi:[0,1,1]
	v_pk_fma_f32 v[98:99], v[246:247], v[14:15], v[98:99] op_sel_hi:[0,1,1]
	v_pk_fma_f32 v[84:85], v[246:247], v[16:17], v[84:85] op_sel_hi:[0,1,1]
	v_pk_fma_f32 v[94:95], v[246:247], v[18:19], v[94:95] op_sel_hi:[0,1,1]
	v_pk_fma_f32 v[96:97], v[246:247], v[20:21], v[96:97] op_sel_hi:[0,1,1]
	v_mfma_f32_32x32x16_f16 v[222:237], v[62:65], v[178:181], v[222:237]
	ds_read_b128 v[178:181], v69 offset:1376
	v_pk_fma_f32 v[90:91], v[246:247], v[22:23], v[90:91] op_sel_hi:[0,1,1]
	v_pk_fma_f32 v[92:93], v[246:247], v[24:25], v[92:93] op_sel_hi:[0,1,1]
	v_pk_fma_f32 v[86:87], v[246:247], v[26:27], v[86:87] op_sel_hi:[0,1,1]
	v_pk_fma_f32 v[88:89], v[246:247], v[28:29], v[88:89] op_sel_hi:[0,1,1]
	v_pk_fma_f32 v[82:83], v[246:247], v[30:31], v[82:83] op_sel_hi:[0,1,1]
	v_pk_fma_f32 v[78:79], v[246:247], v[32:33], v[78:79] op_sel_hi:[0,1,1]
	s_waitcnt lgkmcnt(3)
	v_mfma_f32_32x32x16_f16 v[2:17], v[34:37], v[166:169], 0
	s_nop 1
	v_max_f32_e32 v182, 0, v182
	v_max_f32_e32 v183, 0, v183
	v_max_f32_e32 v184, 0, v184
	v_max_f32_e32 v185, 0, v185
	v_max_f32_e32 v186, 0, v186
	v_max_f32_e32 v187, 0, v187
	v_mfma_f32_32x32x16_f16 v[18:33], v[42:45], v[166:169], 0
	ds_read_b128 v[166:169], v69 offset:1408
	v_max_f32_e32 v188, 0, v188
	v_max_f32_e32 v189, 0, v189
	v_max_f32_e32 v190, 0, v190
	v_max_f32_e32 v191, 0, v191
	v_max_f32_e32 v192, 0, v192
	v_max_f32_e32 v193, 0, v193
	s_waitcnt lgkmcnt(3)
	v_mfma_f32_32x32x16_f16 v[2:17], v[38:41], v[170:173], v[2:17]
	v_max_f32_e32 v194, 0, v194
	v_max_f32_e32 v195, 0, v195
	v_max_f32_e32 v196, 0, v196
	v_max_f32_e32 v197, 0, v197
	v_max_f32_e32 v222, 0, v222
	v_max_f32_e32 v223, 0, v223
	v_mfma_f32_32x32x16_f16 v[18:33], v[46:49], v[170:173], v[18:33]
	ds_read_b128 v[170:173], v69 offset:1440
	v_max_f32_e32 v224, 0, v224
	v_max_f32_e32 v225, 0, v225
	v_max_f32_e32 v226, 0, v226
	v_max_f32_e32 v227, 0, v227
	v_max_f32_e32 v228, 0, v228
	v_max_f32_e32 v229, 0, v229
	s_waitcnt lgkmcnt(3)
	v_mfma_f32_32x32x16_f16 v[2:17], v[50:53], v[174:177], v[2:17]
	v_max_f32_e32 v230, 0, v230
	v_max_f32_e32 v231, 0, v231
	v_max_f32_e32 v232, 0, v232
	v_max_f32_e32 v233, 0, v233
	v_max_f32_e32 v234, 0, v234
	v_max_f32_e32 v235, 0, v235
	v_mfma_f32_32x32x16_f16 v[18:33], v[58:61], v[174:177], v[18:33]
	ds_read_b128 v[174:177], v69 offset:1472
	v_max_f32_e32 v236, 0, v236
	v_max_f32_e32 v237, 0, v237
	v_pk_fma_f32 v[108:109], v[246:247], v[182:183], v[108:109] op_sel:[1,0,0] op_sel_hi:[1,1,1]
	v_pk_fma_f32 v[110:111], v[246:247], v[184:185], v[110:111] op_sel:[1,0,0] op_sel_hi:[1,1,1]
	v_pk_fma_f32 v[104:105], v[246:247], v[186:187], v[104:105] op_sel:[1,0,0] op_sel_hi:[1,1,1]
	v_pk_fma_f32 v[106:107], v[246:247], v[188:189], v[106:107] op_sel:[1,0,0] op_sel_hi:[1,1,1]
	s_waitcnt lgkmcnt(3)
	v_mfma_f32_32x32x16_f16 v[2:17], v[54:57], v[178:181], v[2:17]
	v_pk_fma_f32 v[100:101], v[246:247], v[190:191], v[100:101] op_sel:[1,0,0] op_sel_hi:[1,1,1]
	v_pk_fma_f32 v[102:103], v[246:247], v[192:193], v[102:103] op_sel:[1,0,0] op_sel_hi:[1,1,1]
	v_pk_fma_f32 v[98:99], v[246:247], v[194:195], v[98:99] op_sel:[1,0,0] op_sel_hi:[1,1,1]
	v_pk_fma_f32 v[84:85], v[246:247], v[196:197], v[84:85] op_sel:[1,0,0] op_sel_hi:[1,1,1]
	v_pk_fma_f32 v[94:95], v[246:247], v[222:223], v[94:95] op_sel:[1,0,0] op_sel_hi:[1,1,1]
	v_pk_fma_f32 v[96:97], v[246:247], v[224:225], v[96:97] op_sel:[1,0,0] op_sel_hi:[1,1,1]
	v_mfma_f32_32x32x16_f16 v[18:33], v[62:65], v[178:181], v[18:33]
	ds_read_b128 v[178:181], v69 offset:1504
	v_pk_fma_f32 v[90:91], v[246:247], v[226:227], v[90:91] op_sel:[1,0,0] op_sel_hi:[1,1,1]
	v_pk_fma_f32 v[92:93], v[246:247], v[228:229], v[92:93] op_sel:[1,0,0] op_sel_hi:[1,1,1]
	v_pk_fma_f32 v[86:87], v[246:247], v[230:231], v[86:87] op_sel:[1,0,0] op_sel_hi:[1,1,1]
	v_pk_fma_f32 v[88:89], v[246:247], v[232:233], v[88:89] op_sel:[1,0,0] op_sel_hi:[1,1,1]
	v_pk_fma_f32 v[82:83], v[246:247], v[234:235], v[82:83] op_sel:[1,0,0] op_sel_hi:[1,1,1]
	v_pk_fma_f32 v[78:79], v[246:247], v[236:237], v[78:79] op_sel:[1,0,0] op_sel_hi:[1,1,1]
	s_waitcnt lgkmcnt(3)
	v_mfma_f32_32x32x16_f16 v[182:197], v[34:37], v[166:169], 0
	s_nop 1
	v_max_f32_e32 v2, 0, v2
	v_max_f32_e32 v3, 0, v3
	v_max_f32_e32 v4, 0, v4
	v_max_f32_e32 v5, 0, v5
	v_max_f32_e32 v6, 0, v6
	v_max_f32_e32 v7, 0, v7
	v_mfma_f32_32x32x16_f16 v[222:237], v[42:45], v[166:169], 0
	ds_read_b128 v[166:169], v69 offset:1536
	v_max_f32_e32 v8, 0, v8
	v_max_f32_e32 v9, 0, v9
	v_max_f32_e32 v10, 0, v10
	v_max_f32_e32 v11, 0, v11
	v_max_f32_e32 v12, 0, v12
	v_max_f32_e32 v13, 0, v13
	s_waitcnt lgkmcnt(3)
	v_mfma_f32_32x32x16_f16 v[182:197], v[38:41], v[170:173], v[182:197]
	v_max_f32_e32 v14, 0, v14
	v_max_f32_e32 v15, 0, v15
	v_max_f32_e32 v16, 0, v16
	v_max_f32_e32 v17, 0, v17
	v_max_f32_e32 v18, 0, v18
	v_max_f32_e32 v19, 0, v19
	v_mfma_f32_32x32x16_f16 v[222:237], v[46:49], v[170:173], v[222:237]
	ds_read_b128 v[170:173], v69 offset:1568
	v_max_f32_e32 v20, 0, v20
	v_max_f32_e32 v21, 0, v21
	v_max_f32_e32 v22, 0, v22
	v_max_f32_e32 v23, 0, v23
	v_max_f32_e32 v24, 0, v24
	v_max_f32_e32 v25, 0, v25
	s_waitcnt lgkmcnt(3)
	v_mfma_f32_32x32x16_f16 v[182:197], v[50:53], v[174:177], v[182:197]
	v_max_f32_e32 v26, 0, v26
	v_max_f32_e32 v27, 0, v27
	v_max_f32_e32 v28, 0, v28
	v_max_f32_e32 v29, 0, v29
	v_max_f32_e32 v30, 0, v30
	v_max_f32_e32 v31, 0, v31
	v_mfma_f32_32x32x16_f16 v[222:237], v[58:61], v[174:177], v[222:237]
	ds_read_b128 v[174:177], v69 offset:1600
	v_max_f32_e32 v32, 0, v32
	v_max_f32_e32 v33, 0, v33
	v_pk_fma_f32 v[108:109], v[248:249], v[2:3], v[108:109] op_sel_hi:[0,1,1]
	v_pk_fma_f32 v[110:111], v[248:249], v[4:5], v[110:111] op_sel_hi:[0,1,1]
	v_pk_fma_f32 v[104:105], v[248:249], v[6:7], v[104:105] op_sel_hi:[0,1,1]
	v_pk_fma_f32 v[106:107], v[248:249], v[8:9], v[106:107] op_sel_hi:[0,1,1]
	s_waitcnt lgkmcnt(3)
	v_mfma_f32_32x32x16_f16 v[182:197], v[54:57], v[178:181], v[182:197]
	v_pk_fma_f32 v[100:101], v[248:249], v[10:11], v[100:101] op_sel_hi:[0,1,1]
	v_pk_fma_f32 v[102:103], v[248:249], v[12:13], v[102:103] op_sel_hi:[0,1,1]
	v_pk_fma_f32 v[98:99], v[248:249], v[14:15], v[98:99] op_sel_hi:[0,1,1]
	v_pk_fma_f32 v[84:85], v[248:249], v[16:17], v[84:85] op_sel_hi:[0,1,1]
	v_pk_fma_f32 v[94:95], v[248:249], v[18:19], v[94:95] op_sel_hi:[0,1,1]
	v_pk_fma_f32 v[96:97], v[248:249], v[20:21], v[96:97] op_sel_hi:[0,1,1]
	v_mfma_f32_32x32x16_f16 v[222:237], v[62:65], v[178:181], v[222:237]
	ds_read_b128 v[178:181], v69 offset:1632
	v_pk_fma_f32 v[90:91], v[248:249], v[22:23], v[90:91] op_sel_hi:[0,1,1]
	v_pk_fma_f32 v[92:93], v[248:249], v[24:25], v[92:93] op_sel_hi:[0,1,1]
	v_pk_fma_f32 v[86:87], v[248:249], v[26:27], v[86:87] op_sel_hi:[0,1,1]
	v_pk_fma_f32 v[88:89], v[248:249], v[28:29], v[88:89] op_sel_hi:[0,1,1]
	v_pk_fma_f32 v[82:83], v[248:249], v[30:31], v[82:83] op_sel_hi:[0,1,1]
	v_pk_fma_f32 v[78:79], v[248:249], v[32:33], v[78:79] op_sel_hi:[0,1,1]
	s_waitcnt lgkmcnt(3)
	v_mfma_f32_32x32x16_f16 v[2:17], v[34:37], v[166:169], 0
	s_nop 1
	v_max_f32_e32 v182, 0, v182
	v_max_f32_e32 v183, 0, v183
	v_max_f32_e32 v184, 0, v184
	v_max_f32_e32 v185, 0, v185
	v_max_f32_e32 v186, 0, v186
	v_max_f32_e32 v187, 0, v187
	v_mfma_f32_32x32x16_f16 v[18:33], v[42:45], v[166:169], 0
	ds_read_b128 v[166:169], v69 offset:1664
	v_max_f32_e32 v188, 0, v188
	v_max_f32_e32 v189, 0, v189
	v_max_f32_e32 v190, 0, v190
	v_max_f32_e32 v191, 0, v191
	v_max_f32_e32 v192, 0, v192
	v_max_f32_e32 v193, 0, v193
	s_waitcnt lgkmcnt(3)
	v_mfma_f32_32x32x16_f16 v[2:17], v[38:41], v[170:173], v[2:17]
	v_max_f32_e32 v194, 0, v194
	v_max_f32_e32 v195, 0, v195
	v_max_f32_e32 v196, 0, v196
	v_max_f32_e32 v197, 0, v197
	v_max_f32_e32 v222, 0, v222
	v_max_f32_e32 v223, 0, v223
	v_mfma_f32_32x32x16_f16 v[18:33], v[46:49], v[170:173], v[18:33]
	ds_read_b128 v[170:173], v69 offset:1696
	v_max_f32_e32 v224, 0, v224
	v_max_f32_e32 v225, 0, v225
	v_max_f32_e32 v226, 0, v226
	v_max_f32_e32 v227, 0, v227
	v_max_f32_e32 v228, 0, v228
	v_max_f32_e32 v229, 0, v229
	s_waitcnt lgkmcnt(3)
	v_mfma_f32_32x32x16_f16 v[2:17], v[50:53], v[174:177], v[2:17]
	v_max_f32_e32 v230, 0, v230
	v_max_f32_e32 v231, 0, v231
	v_max_f32_e32 v232, 0, v232
	v_max_f32_e32 v233, 0, v233
	v_max_f32_e32 v234, 0, v234
	v_max_f32_e32 v235, 0, v235
	v_mfma_f32_32x32x16_f16 v[18:33], v[58:61], v[174:177], v[18:33]
	ds_read_b128 v[174:177], v69 offset:1728
	v_max_f32_e32 v236, 0, v236
	v_max_f32_e32 v237, 0, v237
	v_pk_fma_f32 v[108:109], v[248:249], v[182:183], v[108:109] op_sel:[1,0,0] op_sel_hi:[1,1,1]
	v_pk_fma_f32 v[110:111], v[248:249], v[184:185], v[110:111] op_sel:[1,0,0] op_sel_hi:[1,1,1]
	v_pk_fma_f32 v[104:105], v[248:249], v[186:187], v[104:105] op_sel:[1,0,0] op_sel_hi:[1,1,1]
	v_pk_fma_f32 v[106:107], v[248:249], v[188:189], v[106:107] op_sel:[1,0,0] op_sel_hi:[1,1,1]
	s_waitcnt lgkmcnt(3)
	v_mfma_f32_32x32x16_f16 v[2:17], v[54:57], v[178:181], v[2:17]
	v_pk_fma_f32 v[100:101], v[248:249], v[190:191], v[100:101] op_sel:[1,0,0] op_sel_hi:[1,1,1]
	v_pk_fma_f32 v[102:103], v[248:249], v[192:193], v[102:103] op_sel:[1,0,0] op_sel_hi:[1,1,1]
	v_pk_fma_f32 v[98:99], v[248:249], v[194:195], v[98:99] op_sel:[1,0,0] op_sel_hi:[1,1,1]
	v_pk_fma_f32 v[84:85], v[248:249], v[196:197], v[84:85] op_sel:[1,0,0] op_sel_hi:[1,1,1]
	v_pk_fma_f32 v[94:95], v[248:249], v[222:223], v[94:95] op_sel:[1,0,0] op_sel_hi:[1,1,1]
	v_pk_fma_f32 v[96:97], v[248:249], v[224:225], v[96:97] op_sel:[1,0,0] op_sel_hi:[1,1,1]
	v_mfma_f32_32x32x16_f16 v[18:33], v[62:65], v[178:181], v[18:33]
	ds_read_b128 v[178:181], v69 offset:1760
	v_pk_fma_f32 v[90:91], v[248:249], v[226:227], v[90:91] op_sel:[1,0,0] op_sel_hi:[1,1,1]
	v_pk_fma_f32 v[92:93], v[248:249], v[228:229], v[92:93] op_sel:[1,0,0] op_sel_hi:[1,1,1]
	v_pk_fma_f32 v[86:87], v[248:249], v[230:231], v[86:87] op_sel:[1,0,0] op_sel_hi:[1,1,1]
	v_pk_fma_f32 v[88:89], v[248:249], v[232:233], v[88:89] op_sel:[1,0,0] op_sel_hi:[1,1,1]
	v_pk_fma_f32 v[82:83], v[248:249], v[234:235], v[82:83] op_sel:[1,0,0] op_sel_hi:[1,1,1]
	v_pk_fma_f32 v[78:79], v[248:249], v[236:237], v[78:79] op_sel:[1,0,0] op_sel_hi:[1,1,1]
	s_waitcnt lgkmcnt(3)
	v_mfma_f32_32x32x16_f16 v[182:197], v[34:37], v[166:169], 0
	s_nop 1
	v_max_f32_e32 v2, 0, v2
	v_max_f32_e32 v3, 0, v3
	v_max_f32_e32 v4, 0, v4
	v_max_f32_e32 v5, 0, v5
	v_max_f32_e32 v6, 0, v6
	v_max_f32_e32 v7, 0, v7
	v_mfma_f32_32x32x16_f16 v[222:237], v[42:45], v[166:169], 0
	ds_read_b128 v[166:169], v69 offset:1792
	v_max_f32_e32 v8, 0, v8
	v_max_f32_e32 v9, 0, v9
	v_max_f32_e32 v10, 0, v10
	v_max_f32_e32 v11, 0, v11
	v_max_f32_e32 v12, 0, v12
	v_max_f32_e32 v13, 0, v13
	s_waitcnt lgkmcnt(3)
	v_mfma_f32_32x32x16_f16 v[182:197], v[38:41], v[170:173], v[182:197]
	v_max_f32_e32 v14, 0, v14
	v_max_f32_e32 v15, 0, v15
	v_max_f32_e32 v16, 0, v16
	v_max_f32_e32 v17, 0, v17
	v_max_f32_e32 v18, 0, v18
	v_max_f32_e32 v19, 0, v19
	v_mfma_f32_32x32x16_f16 v[222:237], v[46:49], v[170:173], v[222:237]
	ds_read_b128 v[170:173], v69 offset:1824
	v_max_f32_e32 v20, 0, v20
	v_max_f32_e32 v21, 0, v21
	v_max_f32_e32 v22, 0, v22
	v_max_f32_e32 v23, 0, v23
	v_max_f32_e32 v24, 0, v24
	v_max_f32_e32 v25, 0, v25
	s_waitcnt lgkmcnt(3)
	v_mfma_f32_32x32x16_f16 v[182:197], v[50:53], v[174:177], v[182:197]
	v_max_f32_e32 v26, 0, v26
	v_max_f32_e32 v27, 0, v27
	v_max_f32_e32 v28, 0, v28
	v_max_f32_e32 v29, 0, v29
	v_max_f32_e32 v30, 0, v30
	v_max_f32_e32 v31, 0, v31
	v_mfma_f32_32x32x16_f16 v[222:237], v[58:61], v[174:177], v[222:237]
	ds_read_b128 v[174:177], v69 offset:1856
	v_max_f32_e32 v32, 0, v32
	v_max_f32_e32 v33, 0, v33
	v_pk_fma_f32 v[108:109], v[250:251], v[2:3], v[108:109] op_sel_hi:[0,1,1]
	v_pk_fma_f32 v[110:111], v[250:251], v[4:5], v[110:111] op_sel_hi:[0,1,1]
	v_pk_fma_f32 v[104:105], v[250:251], v[6:7], v[104:105] op_sel_hi:[0,1,1]
	v_pk_fma_f32 v[106:107], v[250:251], v[8:9], v[106:107] op_sel_hi:[0,1,1]
	s_waitcnt lgkmcnt(3)
	v_mfma_f32_32x32x16_f16 v[182:197], v[54:57], v[178:181], v[182:197]
	v_pk_fma_f32 v[100:101], v[250:251], v[10:11], v[100:101] op_sel_hi:[0,1,1]
	v_pk_fma_f32 v[102:103], v[250:251], v[12:13], v[102:103] op_sel_hi:[0,1,1]
	v_pk_fma_f32 v[98:99], v[250:251], v[14:15], v[98:99] op_sel_hi:[0,1,1]
	v_pk_fma_f32 v[84:85], v[250:251], v[16:17], v[84:85] op_sel_hi:[0,1,1]
	v_pk_fma_f32 v[94:95], v[250:251], v[18:19], v[94:95] op_sel_hi:[0,1,1]
	v_pk_fma_f32 v[96:97], v[250:251], v[20:21], v[96:97] op_sel_hi:[0,1,1]
	v_mfma_f32_32x32x16_f16 v[222:237], v[62:65], v[178:181], v[222:237]
	ds_read_b128 v[178:181], v69 offset:1888
	v_pk_fma_f32 v[90:91], v[250:251], v[22:23], v[90:91] op_sel_hi:[0,1,1]
	v_pk_fma_f32 v[92:93], v[250:251], v[24:25], v[92:93] op_sel_hi:[0,1,1]
	v_pk_fma_f32 v[86:87], v[250:251], v[26:27], v[86:87] op_sel_hi:[0,1,1]
	v_pk_fma_f32 v[88:89], v[250:251], v[28:29], v[88:89] op_sel_hi:[0,1,1]
	v_pk_fma_f32 v[82:83], v[250:251], v[30:31], v[82:83] op_sel_hi:[0,1,1]
	v_pk_fma_f32 v[78:79], v[250:251], v[32:33], v[78:79] op_sel_hi:[0,1,1]
	s_waitcnt lgkmcnt(3)
	v_mfma_f32_32x32x16_f16 v[2:17], v[34:37], v[166:169], 0
	s_nop 1
	v_max_f32_e32 v182, 0, v182
	v_max_f32_e32 v183, 0, v183
	v_max_f32_e32 v184, 0, v184
	v_max_f32_e32 v185, 0, v185
	v_max_f32_e32 v186, 0, v186
	v_max_f32_e32 v187, 0, v187
	v_mfma_f32_32x32x16_f16 v[18:33], v[42:45], v[166:169], 0
	ds_read_b128 v[166:169], v69 offset:1920
	v_max_f32_e32 v188, 0, v188
	v_max_f32_e32 v189, 0, v189
	v_max_f32_e32 v190, 0, v190
	v_max_f32_e32 v191, 0, v191
	v_max_f32_e32 v192, 0, v192
	v_max_f32_e32 v193, 0, v193
	s_waitcnt lgkmcnt(3)
	v_mfma_f32_32x32x16_f16 v[2:17], v[38:41], v[170:173], v[2:17]
	v_max_f32_e32 v194, 0, v194
	v_max_f32_e32 v195, 0, v195
	v_max_f32_e32 v196, 0, v196
	v_max_f32_e32 v197, 0, v197
	v_max_f32_e32 v222, 0, v222
	v_max_f32_e32 v223, 0, v223
	v_mfma_f32_32x32x16_f16 v[18:33], v[46:49], v[170:173], v[18:33]
	ds_read_b128 v[170:173], v69 offset:1952
	v_max_f32_e32 v224, 0, v224
	v_max_f32_e32 v225, 0, v225
	v_max_f32_e32 v226, 0, v226
	v_max_f32_e32 v227, 0, v227
	v_max_f32_e32 v228, 0, v228
	v_max_f32_e32 v229, 0, v229
	s_waitcnt lgkmcnt(3)
	v_mfma_f32_32x32x16_f16 v[2:17], v[50:53], v[174:177], v[2:17]
	v_max_f32_e32 v230, 0, v230
	v_max_f32_e32 v231, 0, v231
	v_max_f32_e32 v232, 0, v232
	v_max_f32_e32 v233, 0, v233
	v_max_f32_e32 v234, 0, v234
	v_max_f32_e32 v235, 0, v235
	v_mfma_f32_32x32x16_f16 v[18:33], v[58:61], v[174:177], v[18:33]
	ds_read_b128 v[174:177], v69 offset:1984
	v_max_f32_e32 v236, 0, v236
	v_max_f32_e32 v237, 0, v237
	v_pk_fma_f32 v[108:109], v[250:251], v[182:183], v[108:109] op_sel:[1,0,0] op_sel_hi:[1,1,1]
	v_pk_fma_f32 v[110:111], v[250:251], v[184:185], v[110:111] op_sel:[1,0,0] op_sel_hi:[1,1,1]
	v_pk_fma_f32 v[104:105], v[250:251], v[186:187], v[104:105] op_sel:[1,0,0] op_sel_hi:[1,1,1]
	v_pk_fma_f32 v[106:107], v[250:251], v[188:189], v[106:107] op_sel:[1,0,0] op_sel_hi:[1,1,1]
	s_waitcnt lgkmcnt(3)
	v_mfma_f32_32x32x16_f16 v[2:17], v[54:57], v[178:181], v[2:17]
	v_pk_fma_f32 v[100:101], v[250:251], v[190:191], v[100:101] op_sel:[1,0,0] op_sel_hi:[1,1,1]
	v_pk_fma_f32 v[102:103], v[250:251], v[192:193], v[102:103] op_sel:[1,0,0] op_sel_hi:[1,1,1]
	v_pk_fma_f32 v[98:99], v[250:251], v[194:195], v[98:99] op_sel:[1,0,0] op_sel_hi:[1,1,1]
	v_pk_fma_f32 v[84:85], v[250:251], v[196:197], v[84:85] op_sel:[1,0,0] op_sel_hi:[1,1,1]
	v_pk_fma_f32 v[94:95], v[250:251], v[222:223], v[94:95] op_sel:[1,0,0] op_sel_hi:[1,1,1]
	v_pk_fma_f32 v[96:97], v[250:251], v[224:225], v[96:97] op_sel:[1,0,0] op_sel_hi:[1,1,1]
	v_mfma_f32_32x32x16_f16 v[18:33], v[62:65], v[178:181], v[18:33]
	ds_read_b128 v[178:181], v69 offset:2016
	v_pk_fma_f32 v[90:91], v[250:251], v[226:227], v[90:91] op_sel:[1,0,0] op_sel_hi:[1,1,1]
	v_pk_fma_f32 v[92:93], v[250:251], v[228:229], v[92:93] op_sel:[1,0,0] op_sel_hi:[1,1,1]
	v_pk_fma_f32 v[86:87], v[250:251], v[230:231], v[86:87] op_sel:[1,0,0] op_sel_hi:[1,1,1]
	v_pk_fma_f32 v[88:89], v[250:251], v[232:233], v[88:89] op_sel:[1,0,0] op_sel_hi:[1,1,1]
	v_pk_fma_f32 v[82:83], v[250:251], v[234:235], v[82:83] op_sel:[1,0,0] op_sel_hi:[1,1,1]
	v_pk_fma_f32 v[78:79], v[250:251], v[236:237], v[78:79] op_sel:[1,0,0] op_sel_hi:[1,1,1]
	s_waitcnt lgkmcnt(3)
	v_mfma_f32_32x32x16_f16 v[182:197], v[34:37], v[166:169], 0
	s_nop 1
	v_max_f32_e32 v2, 0, v2
	v_max_f32_e32 v3, 0, v3
	v_max_f32_e32 v4, 0, v4
	v_max_f32_e32 v5, 0, v5
	v_max_f32_e32 v6, 0, v6
	v_max_f32_e32 v7, 0, v7
	v_mfma_f32_32x32x16_f16 v[222:237], v[42:45], v[166:169], 0
	v_max_f32_e32 v8, 0, v8
	v_max_f32_e32 v9, 0, v9
	v_max_f32_e32 v10, 0, v10
	v_max_f32_e32 v11, 0, v11
	v_max_f32_e32 v12, 0, v12
	v_max_f32_e32 v13, 0, v13
	s_waitcnt lgkmcnt(2)
	v_mfma_f32_32x32x16_f16 v[182:197], v[38:41], v[170:173], v[182:197]
	v_max_f32_e32 v14, 0, v14
	v_max_f32_e32 v15, 0, v15
	v_max_f32_e32 v16, 0, v16
	v_max_f32_e32 v17, 0, v17
	v_max_f32_e32 v18, 0, v18
	v_max_f32_e32 v19, 0, v19
	v_mfma_f32_32x32x16_f16 v[222:237], v[46:49], v[170:173], v[222:237]
	v_max_f32_e32 v20, 0, v20
	v_max_f32_e32 v21, 0, v21
	v_max_f32_e32 v22, 0, v22
	v_max_f32_e32 v23, 0, v23
	v_max_f32_e32 v24, 0, v24
	v_max_f32_e32 v25, 0, v25
	s_waitcnt lgkmcnt(1)
	v_mfma_f32_32x32x16_f16 v[182:197], v[50:53], v[174:177], v[182:197]
	v_max_f32_e32 v26, 0, v26
	v_max_f32_e32 v27, 0, v27
	v_max_f32_e32 v28, 0, v28
	v_max_f32_e32 v29, 0, v29
	v_max_f32_e32 v30, 0, v30
	v_max_f32_e32 v31, 0, v31
	v_mfma_f32_32x32x16_f16 v[222:237], v[58:61], v[174:177], v[222:237]
	v_max_f32_e32 v32, 0, v32
	v_max_f32_e32 v33, 0, v33
	v_pk_fma_f32 v[108:109], v[252:253], v[2:3], v[108:109] op_sel_hi:[0,1,1]
	v_pk_fma_f32 v[110:111], v[252:253], v[4:5], v[110:111] op_sel_hi:[0,1,1]
	v_pk_fma_f32 v[104:105], v[252:253], v[6:7], v[104:105] op_sel_hi:[0,1,1]
	v_pk_fma_f32 v[106:107], v[252:253], v[8:9], v[106:107] op_sel_hi:[0,1,1]
	s_waitcnt lgkmcnt(0)
	v_mfma_f32_32x32x16_f16 v[182:197], v[54:57], v[178:181], v[182:197]
	v_pk_fma_f32 v[100:101], v[252:253], v[10:11], v[100:101] op_sel_hi:[0,1,1]
	v_pk_fma_f32 v[102:103], v[252:253], v[12:13], v[102:103] op_sel_hi:[0,1,1]
	v_pk_fma_f32 v[98:99], v[252:253], v[14:15], v[98:99] op_sel_hi:[0,1,1]
	v_pk_fma_f32 v[84:85], v[252:253], v[16:17], v[84:85] op_sel_hi:[0,1,1]
	v_pk_fma_f32 v[94:95], v[252:253], v[18:19], v[94:95] op_sel_hi:[0,1,1]
	v_pk_fma_f32 v[96:97], v[252:253], v[20:21], v[96:97] op_sel_hi:[0,1,1]
	v_mfma_f32_32x32x16_f16 v[222:237], v[62:65], v[178:181], v[222:237]
	v_pk_fma_f32 v[90:91], v[252:253], v[22:23], v[90:91] op_sel_hi:[0,1,1]
	v_pk_fma_f32 v[92:93], v[252:253], v[24:25], v[92:93] op_sel_hi:[0,1,1]
	v_pk_fma_f32 v[86:87], v[252:253], v[26:27], v[86:87] op_sel_hi:[0,1,1]
	v_pk_fma_f32 v[88:89], v[252:253], v[28:29], v[88:89] op_sel_hi:[0,1,1]
	v_pk_fma_f32 v[82:83], v[252:253], v[30:31], v[82:83] op_sel_hi:[0,1,1]
	v_pk_fma_f32 v[78:79], v[252:253], v[32:33], v[78:79] op_sel_hi:[0,1,1]
	s_setprio 0
	s_nop 9
	v_max_f32_e32 v182, 0, v182
	v_max_f32_e32 v183, 0, v183
	v_max_f32_e32 v184, 0, v184
	v_max_f32_e32 v185, 0, v185
	v_max_f32_e32 v186, 0, v186
	v_max_f32_e32 v187, 0, v187
	v_max_f32_e32 v188, 0, v188
	v_max_f32_e32 v189, 0, v189
	v_max_f32_e32 v190, 0, v190
	v_max_f32_e32 v191, 0, v191
	v_max_f32_e32 v192, 0, v192
	v_max_f32_e32 v193, 0, v193
	v_max_f32_e32 v194, 0, v194
	v_max_f32_e32 v195, 0, v195
	v_max_f32_e32 v196, 0, v196
	v_max_f32_e32 v197, 0, v197
	v_max_f32_e32 v222, 0, v222
	v_max_f32_e32 v223, 0, v223
	v_max_f32_e32 v224, 0, v224
	v_max_f32_e32 v225, 0, v225
	v_max_f32_e32 v226, 0, v226
	v_max_f32_e32 v227, 0, v227
	v_max_f32_e32 v228, 0, v228
	v_max_f32_e32 v229, 0, v229
	v_max_f32_e32 v230, 0, v230
	v_max_f32_e32 v231, 0, v231
	v_max_f32_e32 v232, 0, v232
	v_max_f32_e32 v233, 0, v233
	v_max_f32_e32 v234, 0, v234
	v_max_f32_e32 v235, 0, v235
	v_max_f32_e32 v236, 0, v236
	v_max_f32_e32 v237, 0, v237
	v_pk_fma_f32 v[108:109], v[252:253], v[182:183], v[108:109] op_sel:[1,0,0] op_sel_hi:[1,1,1]
	v_pk_fma_f32 v[110:111], v[252:253], v[184:185], v[110:111] op_sel:[1,0,0] op_sel_hi:[1,1,1]
	v_pk_fma_f32 v[104:105], v[252:253], v[186:187], v[104:105] op_sel:[1,0,0] op_sel_hi:[1,1,1]
	v_pk_fma_f32 v[106:107], v[252:253], v[188:189], v[106:107] op_sel:[1,0,0] op_sel_hi:[1,1,1]
	v_pk_fma_f32 v[100:101], v[252:253], v[190:191], v[100:101] op_sel:[1,0,0] op_sel_hi:[1,1,1]
	v_pk_fma_f32 v[102:103], v[252:253], v[192:193], v[102:103] op_sel:[1,0,0] op_sel_hi:[1,1,1]
	v_pk_fma_f32 v[98:99], v[252:253], v[194:195], v[98:99] op_sel:[1,0,0] op_sel_hi:[1,1,1]
	v_pk_fma_f32 v[84:85], v[252:253], v[196:197], v[84:85] op_sel:[1,0,0] op_sel_hi:[1,1,1]
	v_pk_fma_f32 v[94:95], v[252:253], v[222:223], v[94:95] op_sel:[1,0,0] op_sel_hi:[1,1,1]
	v_pk_fma_f32 v[96:97], v[252:253], v[224:225], v[96:97] op_sel:[1,0,0] op_sel_hi:[1,1,1]
	v_pk_fma_f32 v[90:91], v[252:253], v[226:227], v[90:91] op_sel:[1,0,0] op_sel_hi:[1,1,1]
	v_pk_fma_f32 v[92:93], v[252:253], v[228:229], v[92:93] op_sel:[1,0,0] op_sel_hi:[1,1,1]
	v_pk_fma_f32 v[86:87], v[252:253], v[230:231], v[86:87] op_sel:[1,0,0] op_sel_hi:[1,1,1]
	v_pk_fma_f32 v[88:89], v[252:253], v[232:233], v[88:89] op_sel:[1,0,0] op_sel_hi:[1,1,1]
	v_pk_fma_f32 v[82:83], v[252:253], v[234:235], v[82:83] op_sel:[1,0,0] op_sel_hi:[1,1,1]
	v_pk_fma_f32 v[78:79], v[252:253], v[236:237], v[78:79] op_sel:[1,0,0] op_sel_hi:[1,1,1]
	v_ashrrev_i32_e32 v81, 31, v80
	v_lshl_add_u64 v[2:3], v[80:81], 2, v[76:77]
	v_pk_add_f32 v[4:5], v[108:109], 0 op_sel_hi:[1,0]
	v_pk_add_f32 v[6:7], v[110:111], 0 op_sel_hi:[1,0]
	global_store_dwordx4 v[2:3], v[4:7], off
	v_lshlrev_b32_e32 v8, 1, v149
	v_cmp_gt_i32_e64 s[8:9], s21, v8
	v_pk_add_f32 v[4:5], v[104:105], 0 op_sel_hi:[1,0]
	v_pk_add_f32 v[6:7], v[106:107], 0 op_sel_hi:[1,0]
	global_store_dwordx4 v[2:3], v[4:7], off offset:32
	s_nop 1
	v_pk_add_f32 v[4:5], v[100:101], 0 op_sel_hi:[1,0]
	v_pk_add_f32 v[6:7], v[102:103], 0 op_sel_hi:[1,0]
	global_store_dwordx4 v[2:3], v[4:7], off offset:64
	s_nop 1
	v_pk_add_f32 v[4:5], v[98:99], 0 op_sel_hi:[1,0]
	v_pk_add_f32 v[6:7], v[84:85], 0 op_sel_hi:[1,0]
	global_store_dwordx4 v[2:3], v[4:7], off offset:96
	s_and_saveexec_b64 s[10:11], s[8:9]
	s_cbranch_execz .LBB0_613
	v_pk_add_f32 v[4:5], v[94:95], 0 op_sel_hi:[1,0]
	v_pk_add_f32 v[6:7], v[96:97], 0 op_sel_hi:[1,0]
	global_store_dwordx4 v[2:3], v[4:7], off offset:128
	s_nop 1
	v_pk_add_f32 v[4:5], v[90:91], 0 op_sel_hi:[1,0]
	v_pk_add_f32 v[6:7], v[92:93], 0 op_sel_hi:[1,0]
	global_store_dwordx4 v[2:3], v[4:7], off offset:160
	s_nop 1
	v_pk_add_f32 v[4:5], v[86:87], 0 op_sel_hi:[1,0]
	v_pk_add_f32 v[6:7], v[88:89], 0 op_sel_hi:[1,0]
	global_store_dwordx4 v[2:3], v[4:7], off offset:192
	s_nop 1
	v_pk_add_f32 v[4:5], v[82:83], 0 op_sel_hi:[1,0]
	v_pk_add_f32 v[6:7], v[78:79], 0 op_sel_hi:[1,0]
	global_store_dwordx4 v[2:3], v[4:7], off offset:224
	s_branch .LBB0_613
